# HGRN: per-row sum-of-squares reduced with DPP row ops instead of 16 serial ds_bpermute round trips
# speedup vs baseline: 1.0490x; 1.0020x over previous
; #define LAS __attribute__((address_space(3)))
; DI unsigned pk2(float a, float b) { typedef __bf16 bf2 __attribute__((ext_vector_type(2))); bf2 v; v[0] = (__bf16)a; v[1] = (__bf16)b; return __builtin_bit_cast(unsigned, v); }
; DI float bf2f(bf16_t v) { return __uint_as_float(((unsigned)v) << 16); }
; DI void lds_barrier() { asm volatile("s_waitcnt lgkmcnt(0)\n\ts_barrier" ::: "memory"); }
; #define MFMA16(a, b, c) __builtin_amdgcn_mfma_f32_16x16x32_bf16((a), (b), (c), 0, 0, 0)
; DI void hgrn_scan_phase(int wv, const P& p_, LAS unsigned char* lds, float* sumsq) {
;     ...
;           for (int j = 0; j < 4; ++j) {
;             const float k0 = bf2f((bf16_t)kv[2 * j]), k1 = bf2f((bf16_t)kv[2 * j + 1]);
;             const float b0 = j < 2 ? c0[2 * j] : c1[2 * j - 4], b1 = j < 2 ? c0[2 * j + 1] : c1[2 * j - 3];
;             const float rr0 = j < 2 ? r0[2 * j] : r1[2 * j - 4], rr1 = j < 2 ? r0[2 * j + 1] : r1[2 * j - 3];
;             bk[j] = pk2(k0 * __builtin_amdgcn_exp2f(fminf(rr0 - b0, 115.f)), k1 * __builtin_amdgcn_exp2f(fminf(rr1 - b1, 115.f)));
;           }
;           if (jj == 0) a0 = MFMA16(__builtin_bit_cast(bf16x8, aq), __builtin_bit_cast(bf16x8, bk), a0);
;           else a1 = MFMA16(__builtin_bit_cast(bf16x8, aq), __builtin_bit_cast(bf16x8, bk), a1);
;         }
;       }
; #pragma unroll
;       for (int jj = 0; jj < 2; ++jj) { const int J = J0 + jj;
; #pragma unroll
;         for (int reg = 0; reg < 4; ++reg) { const int tt = 16 * mt + 4 * fq + reg, ss = 16 * J + fr; const float v = jj == 0 ? a0[reg] : a1[reg];
;           AB[tt * 72 + ss] = (J <= mt && ss <= tt) ? f2bf(v) : (bf16_t)0; } }
;       lds_barrier();
; #pragma unroll
;       for (int k2 = 0; k2 < 2; ++k2) {
;         const bf16x8 af = *(const LAS bf16x8*)(AB + (16 * mt + fr) * 72 + 32 * k2 + 8 * fq);
;         const bf16x8 vb = *(const LAS bf16x8*)(VT + (16 * vt + fr) * 72 + 32 * k2 + 8 * fq);
;         oacc = MFMA16(af, vb, oacc);
;       }
; #pragma unroll
;       for (int reg = 0; reg < 4; ++reg) {
;         const int tok = b * SEQ + c * 64 + 16 * mt + 4 * fq + reg; const float v = oacc[reg];
;         oraw[(size_t)tok * 1024 + hh * 128 + vq * 32 + 16 * vt + fr] = f2bf(v);
;         float sq = v * v; sq += __shfl_xor(sq, 1); sq += __shfl_xor(sq, 2); sq += __shfl_xor(sq, 4); sq += __shfl_xor(sq, 8);
;         if (fr == 0) atomicAdd(sumsq + (size_t)tok * 8 + hh, sq);
;       }
.LBB0_466:
	s_or_b64 exec, exec, vcc
	v_exp_f32_e32 v33, v56
	v_exp_f32_e32 v56, v57
	v_exp_f32_e32 v57, v58
	v_mul_f32_e32 v33, v33, v34
	v_mul_f32_e32 v34, v56, v35
	v_exp_f32_e32 v35, v59
	v_cvt_pk_bf16_f32 v56, v33, v34
	v_mul_f32_e32 v33, v57, v112
	v_exp_f32_e32 v34, v52
	v_mul_f32_e32 v35, v35, v113
	v_cvt_pk_bf16_f32 v57, v33, v35
	v_exp_f32_e32 v33, v53
	v_exp_f32_e32 v35, v54
	v_exp_f32_e32 v52, v55
	v_mul_f32_e32 v34, v34, v114
	v_mul_f32_e32 v33, v33, v115
	v_cvt_pk_bf16_f32 v58, v34, v33
	v_mul_f32_e32 v33, v35, v116
	v_mul_f32_e32 v34, v52, v117
	v_cvt_pk_bf16_f32 v59, v33, v34
	v_cvt_pk_bf16_f32 v33, v40, s0
	v_cndmask_b32_e64 v33, v33, 0, s[4:5]
	ds_write_b16 v143, v33
	v_cvt_pk_bf16_f32 v33, v41, s0
	v_cndmask_b32_e64 v33, v33, 0, s[68:69]
	ds_write_b16 v143, v33 offset:144
	v_cvt_pk_bf16_f32 v33, v42, s0
	v_cndmask_b32_e64 v33, v33, 0, s[72:73]
	ds_write_b16 v143, v33 offset:288
	v_cvt_pk_bf16_f32 v33, v43, s0
	v_cndmask_b32_e64 v33, v33, 0, s[74:75]
	ds_write_b16 v143, v33 offset:432
	v_cvt_pk_bf16_f32 v33, v44, s0
	v_cndmask_b32_e64 v33, v33, 0, s[62:63]
	ds_write_b16 v130, v33
	v_cvt_pk_bf16_f32 v33, v45, s0
	v_cndmask_b32_e64 v33, v33, 0, s[82:83]
	ds_write_b16 v131, v33
	v_cvt_pk_bf16_f32 v33, v46, s0
	v_cndmask_b32_e64 v33, v33, 0, s[90:91]
	ds_write_b16 v132, v33
	v_cvt_pk_bf16_f32 v33, v47, s0
	v_cndmask_b32_e64 v33, v33, 0, s[0:1]
	ds_write_b16 v133, v33
	s_waitcnt lgkmcnt(0)
	s_barrier
	ds_read_b128 v[40:43], v123
	s_waitcnt lgkmcnt(9)
	v_mfma_f32_16x16x32_bf16 v[44:47], v[56:59], v[72:75], v[48:51]
	s_nop 2
	ds_read_b128 v[48:51], v123 offset:64
	ds_read_b128 v[52:55], v124
	ds_read_b128 v[56:59], v124 offset:64
	s_waitcnt lgkmcnt(1)
	v_mfma_f32_16x16x32_bf16 v[40:43], v[40:43], v[52:55], v[44:47]
	s_waitcnt lgkmcnt(0)
	v_mfma_f32_16x16x32_bf16 v[40:43], v[48:51], v[56:59], v[40:43]
	v_add_u32_e32 v34, -3, v102
	v_ashrrev_i32_e32 v35, 31, v34
	v_lshlrev_b64 v[48:49], 11, v[34:35]
	v_lshl_add_u64 v[48:49], v[108:109], 0, v[48:49]
	v_add_u32_e32 v50, -2, v102
	v_ashrrev_i32_e32 v51, 31, v50
	v_lshlrev_b64 v[52:53], 11, v[50:51]
	v_lshl_add_u64 v[52:53], v[108:109], 0, v[52:53]
	v_add_u32_e32 v54, -1, v102
	v_ashrrev_i32_e32 v55, 31, v54
	v_lshlrev_b64 v[56:57], 11, v[54:55]
	v_lshl_add_u64 v[56:57], v[108:109], 0, v[56:57]
	v_ashrrev_i32_e32 v103, 31, v102
	v_lshlrev_b64 v[58:59], 11, v[102:103]
	v_lshl_add_u64 v[58:59], v[108:109], 0, v[58:59]
	v_mul_f32_e32 v44, v40, v40
	v_mul_f32_e32 v45, v41, v41
	v_mul_f32_e32 v46, v42, v42
	v_mul_f32_e32 v47, v43, v43
	v_cvt_pk_bf16_f32 v33, v40, s0
	v_add_f32_dpp v44, v44, v44 quad_perm:[1,0,3,2] row_mask:0xf bank_mask:0xf
	v_add_f32_dpp v45, v45, v45 quad_perm:[1,0,3,2] row_mask:0xf bank_mask:0xf
	v_add_f32_dpp v46, v46, v46 quad_perm:[1,0,3,2] row_mask:0xf bank_mask:0xf
	v_add_f32_dpp v47, v47, v47 quad_perm:[1,0,3,2] row_mask:0xf bank_mask:0xf
	global_store_short v[48:49], v33, off
	v_add_f32_dpp v44, v44, v44 quad_perm:[2,3,0,1] row_mask:0xf bank_mask:0xf
	v_add_f32_dpp v45, v45, v45 quad_perm:[2,3,0,1] row_mask:0xf bank_mask:0xf
	v_add_f32_dpp v46, v46, v46 quad_perm:[2,3,0,1] row_mask:0xf bank_mask:0xf
	v_add_f32_dpp v47, v47, v47 quad_perm:[2,3,0,1] row_mask:0xf bank_mask:0xf
	v_cvt_pk_bf16_f32 v33, v41, s0
	v_add_f32_dpp v44, v44, v44 row_ror:4 row_mask:0xf bank_mask:0xf
	v_add_f32_dpp v45, v45, v45 row_ror:4 row_mask:0xf bank_mask:0xf
	v_add_f32_dpp v46, v46, v46 row_ror:4 row_mask:0xf bank_mask:0xf
	v_add_f32_dpp v47, v47, v47 row_ror:4 row_mask:0xf bank_mask:0xf
	global_store_short v[52:53], v33, off
	v_add_f32_dpp v44, v44, v44 row_ror:8 row_mask:0xf bank_mask:0xf
	v_add_f32_dpp v45, v45, v45 row_ror:8 row_mask:0xf bank_mask:0xf
	v_add_f32_dpp v46, v46, v46 row_ror:8 row_mask:0xf bank_mask:0xf
	v_add_f32_dpp v47, v47, v47 row_ror:8 row_mask:0xf bank_mask:0xf
	v_cvt_pk_bf16_f32 v33, v42, s0
	v_cvt_pk_bf16_f32 v40, v43, s0
	global_store_short v[56:57], v33, off
	global_store_short v[58:59], v40, off
	s_and_saveexec_b64 vcc, s[14:15]
	s_cbranch_execz .LBB0_441
	v_lshlrev_b64 v[34:35], 5, v[34:35]
	v_lshl_add_u64 v[34:35], s[60:61], 0, v[34:35]
	global_atomic_add_f32 v[34:35], v44, off
	v_lshlrev_b64 v[50:51], 5, v[50:51]
	v_lshl_add_u64 v[50:51], s[60:61], 0, v[50:51]
	global_atomic_add_f32 v[50:51], v45, off
	v_lshlrev_b64 v[54:55], 5, v[54:55]
	v_lshl_add_u64 v[54:55], s[60:61], 0, v[54:55]
	global_atomic_add_f32 v[54:55], v46, off
	v_lshlrev_b64 v[48:49], 5, v[102:103]
	v_lshl_add_u64 v[48:49], s[60:61], 0, v[48:49]
	global_atomic_add_f32 v[48:49], v47, off
	s_branch .LBB0_441
